# variant: write-through (sc1) stores in the hand-written P7 and P10 prompt epilogues so the following barrier has less dirty L2 to flush
# speedup vs baseline: 1.0085x; 1.0085x over previous
;     __device__ __forceinline__ void operator()(const f32x4 (&acc)[2][2][4][2], const Unit& u, int wr, int wc, int fr, int fq) const {
;     ...
;         f32x4 gv[2][2];
; #pragma unroll
;         for (int bj = 0; bj < 2; ++bj)
; #pragma unroll
;             for (int n = 0; n < 2; ++n) gv[bj][n] = *(const f32x4*)(gate + (size_t)128 * NMOD + col0 + bj * HALF + n * 16);
;         int roff = row0 * D + col0; asm volatile("" : "+v"(roff));
; #pragma unroll
;         for (int am = 0; am < 4; ++am) { f32x4 rv[2][2][2];
; #pragma unroll
;             for (int m2 = 0; m2 < 2; ++m2)
; #pragma unroll
;                 for (int bj = 0; bj < 2; ++bj)
; #pragma unroll
;                     for (int n = 0; n < 2; ++n) rv[m2][bj][n] = *(const f32x4*)(res0 + (roff + ((am >> 1) * HALF + ((am & 1) * 2 + m2) * 16) * D + bj * HALF + n * 16));
; #pragma unroll
;             for (int m2 = 0; m2 < 2; ++m2)
; #pragma unroll
;                 for (int bj = 0; bj < 2; ++bj)
; #pragma unroll
;                     for (int n = 0; n < 2; ++n) *(f32x4*)(out + (roff + ((am >> 1) * HALF + ((am & 1) * 2 + m2) * 16) * D + bj * HALF + n * 16)) = rv[m2][bj][n] + gv[bj][n] * acc[am >> 1][bj][(am & 1) * 2 + m2][n]; }
.LBB0_886:
	v_ashrrev_i32_e32 v163, 31, v162
	v_lshl_add_u64 v[128:129], v[162:163], 2, s[12:13]
	v_lshl_add_u32 v164, v168, 11, v162
	global_load_dwordx4 v[140:143], v[128:129], off
	global_load_dwordx4 v[136:139], v[128:129], off offset:64
	global_load_dwordx4 v[132:135], v[128:129], off offset:512
	s_nop 0
	global_load_dwordx4 v[128:131], v[128:129], off offset:576
	v_readlane_b32 s64, v245, 37
	v_readlane_b32 s65, v245, 38
	v_readlane_b32 s66, v245, 39
	v_readlane_b32 s67, v245, 40
	v_readlane_b32 s68, v245, 41
	v_readlane_b32 s69, v245, 42
	v_readlane_b32 s70, v245, 43
	v_readlane_b32 s71, v245, 44
	v_readlane_b32 s72, v245, 45
	v_readlane_b32 s73, v245, 46
	v_readlane_b32 s74, v245, 47
	v_readlane_b32 s75, v245, 48
	v_readlane_b32 s76, v245, 49
	v_readlane_b32 s77, v245, 50
	v_readlane_b32 s78, v245, 51
	v_readlane_b32 s79, v245, 52
	v_ashrrev_i32_e32 v165, 31, v164
	v_lshlrev_b64 v[222:223], 2, v[164:165]
	s_nop 1
	v_lshl_add_u64 v[220:221], s[64:65], 0, v[222:223]
	v_lshl_add_u64 v[222:223], s[6:7], 0, v[222:223]
	global_load_dwordx4 v[172:175], v[220:221], off
	global_load_dwordx4 v[176:179], v[220:221], off offset:64
	global_load_dwordx4 v[180:183], v[220:221], off offset:512
	global_load_dwordx4 v[184:187], v[220:221], off offset:576
	v_add_co_u32_e32 v224, vcc, 0x20000, v220
	s_nop 1
	v_addc_co_u32_e32 v225, vcc, 0, v221, vcc
	global_load_dwordx4 v[188:191], v[224:225], off
	global_load_dwordx4 v[192:195], v[224:225], off offset:64
	global_load_dwordx4 v[196:199], v[224:225], off offset:512
	global_load_dwordx4 v[200:203], v[224:225], off offset:576
	v_add_co_u32_e32 v224, vcc, 0x40000, v220
	s_nop 1
	v_addc_co_u32_e32 v225, vcc, 0, v221, vcc
	global_load_dwordx4 v[204:207], v[224:225], off
	global_load_dwordx4 v[208:211], v[224:225], off offset:64
	global_load_dwordx4 v[212:215], v[224:225], off offset:512
	global_load_dwordx4 v[216:219], v[224:225], off offset:576
	s_waitcnt vmcnt(8)
	v_pk_fma_f32 v[174:175], v[126:127], v[142:143], v[174:175]
	v_pk_fma_f32 v[172:173], v[124:125], v[140:141], v[172:173]
	global_store_dwordx4 v[222:223], v[172:175], off sc1
	v_pk_fma_f32 v[178:179], v[122:123], v[138:139], v[178:179]
	v_pk_fma_f32 v[176:177], v[120:121], v[136:137], v[176:177]
	global_store_dwordx4 v[222:223], v[176:179], off offset:64 sc1
	v_pk_fma_f32 v[182:183], v[110:111], v[134:135], v[182:183]
	v_pk_fma_f32 v[180:181], v[108:109], v[132:133], v[180:181]
	global_store_dwordx4 v[222:223], v[180:183], off offset:512 sc1
	v_pk_fma_f32 v[186:187], v[106:107], v[130:131], v[186:187]
	v_pk_fma_f32 v[184:185], v[104:105], v[128:129], v[184:185]
	global_store_dwordx4 v[222:223], v[184:187], off offset:576 sc1
	v_add_co_u32_e32 v224, vcc, 0x60000, v220
	s_nop 1
	v_addc_co_u32_e32 v225, vcc, 0, v221, vcc
	global_load_dwordx4 v[172:175], v[224:225], off
	global_load_dwordx4 v[176:179], v[224:225], off offset:64
	global_load_dwordx4 v[180:183], v[224:225], off offset:512
	global_load_dwordx4 v[184:187], v[224:225], off offset:576
	s_waitcnt vmcnt(12)
	v_add_co_u32_e32 v226, vcc, 0x20000, v222
	s_nop 1
	v_addc_co_u32_e32 v227, vcc, 0, v223, vcc
	v_pk_fma_f32 v[190:191], v[118:119], v[142:143], v[190:191]
	v_pk_fma_f32 v[188:189], v[116:117], v[140:141], v[188:189]
	global_store_dwordx4 v[226:227], v[188:191], off sc1
	v_pk_fma_f32 v[194:195], v[114:115], v[138:139], v[194:195]
	v_pk_fma_f32 v[192:193], v[112:113], v[136:137], v[192:193]
	global_store_dwordx4 v[226:227], v[192:195], off offset:64 sc1
	v_pk_fma_f32 v[198:199], v[102:103], v[134:135], v[198:199]
	v_pk_fma_f32 v[196:197], v[100:101], v[132:133], v[196:197]
	global_store_dwordx4 v[226:227], v[196:199], off offset:512 sc1
	v_pk_fma_f32 v[202:203], v[98:99], v[130:131], v[202:203]
	v_pk_fma_f32 v[200:201], v[96:97], v[128:129], v[200:201]
	global_store_dwordx4 v[226:227], v[200:203], off offset:576 sc1
	v_add_co_u32_e32 v224, vcc, 0x100000, v220
	s_nop 1
	v_addc_co_u32_e32 v225, vcc, 0, v221, vcc
	global_load_dwordx4 v[188:191], v[224:225], off
	global_load_dwordx4 v[192:195], v[224:225], off offset:64
	global_load_dwordx4 v[196:199], v[224:225], off offset:512
	global_load_dwordx4 v[200:203], v[224:225], off offset:576
	s_waitcnt vmcnt(16)
	v_add_co_u32_e32 v226, vcc, 0x40000, v222
	s_nop 1
	v_addc_co_u32_e32 v227, vcc, 0, v223, vcc
	v_pk_fma_f32 v[206:207], v[94:95], v[142:143], v[206:207]
	v_pk_fma_f32 v[204:205], v[92:93], v[140:141], v[204:205]
	global_store_dwordx4 v[226:227], v[204:207], off sc1
	v_pk_fma_f32 v[210:211], v[90:91], v[138:139], v[210:211]
	v_pk_fma_f32 v[208:209], v[88:89], v[136:137], v[208:209]
	global_store_dwordx4 v[226:227], v[208:211], off offset:64 sc1
	v_pk_fma_f32 v[214:215], v[78:79], v[134:135], v[214:215]
	v_pk_fma_f32 v[212:213], v[76:77], v[132:133], v[212:213]
	global_store_dwordx4 v[226:227], v[212:215], off offset:512 sc1
	v_pk_fma_f32 v[218:219], v[74:75], v[130:131], v[218:219]
	v_pk_fma_f32 v[216:217], v[72:73], v[128:129], v[216:217]
	global_store_dwordx4 v[226:227], v[216:219], off offset:576 sc1
	v_add_co_u32_e32 v224, vcc, 0x120000, v220
	s_nop 1
	v_addc_co_u32_e32 v225, vcc, 0, v221, vcc
	global_load_dwordx4 v[204:207], v[224:225], off
	global_load_dwordx4 v[208:211], v[224:225], off offset:64
	global_load_dwordx4 v[212:215], v[224:225], off offset:512
	global_load_dwordx4 v[216:219], v[224:225], off offset:576
	s_waitcnt vmcnt(16)
;     __device__ __forceinline__ void operator()(const f32x4 (&acc)[2][2][4][2], const Unit& u, int wr, int wc, int fr, int fq) const {
;     ...
;         for (int am = 0; am < 4; ++am) { f32x4 rv[2][2][2];
; #pragma unroll
;             for (int m2 = 0; m2 < 2; ++m2)
; #pragma unroll
;                 for (int bj = 0; bj < 2; ++bj)
; #pragma unroll
;                     for (int n = 0; n < 2; ++n) rv[m2][bj][n] = *(const f32x4*)(res0 + (roff + ((am >> 1) * HALF + ((am & 1) * 2 + m2) * 16) * D + bj * HALF + n * 16));
; #pragma unroll
;             for (int m2 = 0; m2 < 2; ++m2)
; #pragma unroll
;                 for (int bj = 0; bj < 2; ++bj)
; #pragma unroll
;                     for (int n = 0; n < 2; ++n) *(f32x4*)(out + (roff + ((am >> 1) * HALF + ((am & 1) * 2 + m2) * 16) * D + bj * HALF + n * 16)) = rv[m2][bj][n] + gv[bj][n] * acc[am >> 1][bj][(am & 1) * 2 + m2][n]; }
	v_add_co_u32_e32 v226, vcc, 0x60000, v222
	s_nop 1
	v_addc_co_u32_e32 v227, vcc, 0, v223, vcc
	v_pk_fma_f32 v[174:175], v[86:87], v[142:143], v[174:175]
	v_pk_fma_f32 v[172:173], v[84:85], v[140:141], v[172:173]
	global_store_dwordx4 v[226:227], v[172:175], off sc1
	v_pk_fma_f32 v[178:179], v[82:83], v[138:139], v[178:179]
	v_pk_fma_f32 v[176:177], v[80:81], v[136:137], v[176:177]
	global_store_dwordx4 v[226:227], v[176:179], off offset:64 sc1
	v_pk_fma_f32 v[182:183], v[70:71], v[134:135], v[182:183]
	v_pk_fma_f32 v[180:181], v[68:69], v[132:133], v[180:181]
	global_store_dwordx4 v[226:227], v[180:183], off offset:512 sc1
	v_pk_fma_f32 v[186:187], v[66:67], v[130:131], v[186:187]
	v_pk_fma_f32 v[184:185], v[64:65], v[128:129], v[184:185]
	global_store_dwordx4 v[226:227], v[184:187], off offset:576 sc1
	v_add_co_u32_e32 v224, vcc, 0x140000, v220
	s_nop 1
	v_addc_co_u32_e32 v225, vcc, 0, v221, vcc
	global_load_dwordx4 v[172:175], v[224:225], off
	global_load_dwordx4 v[176:179], v[224:225], off offset:64
	global_load_dwordx4 v[180:183], v[224:225], off offset:512
	global_load_dwordx4 v[184:187], v[224:225], off offset:576
	s_waitcnt vmcnt(16)
	v_add_co_u32_e32 v226, vcc, 0x100000, v222
	s_nop 1
	v_addc_co_u32_e32 v227, vcc, 0, v223, vcc
	v_pk_fma_f32 v[190:191], v[62:63], v[142:143], v[190:191]
	v_pk_fma_f32 v[188:189], v[60:61], v[140:141], v[188:189]
	global_store_dwordx4 v[226:227], v[188:191], off sc1
	v_pk_fma_f32 v[194:195], v[58:59], v[138:139], v[194:195]
	v_pk_fma_f32 v[192:193], v[56:57], v[136:137], v[192:193]
	global_store_dwordx4 v[226:227], v[192:195], off offset:64 sc1
	v_pk_fma_f32 v[198:199], v[46:47], v[134:135], v[198:199]
	v_pk_fma_f32 v[196:197], v[44:45], v[132:133], v[196:197]
	global_store_dwordx4 v[226:227], v[196:199], off offset:512 sc1
	v_pk_fma_f32 v[202:203], v[42:43], v[130:131], v[202:203]
	v_pk_fma_f32 v[200:201], v[40:41], v[128:129], v[200:201]
	global_store_dwordx4 v[226:227], v[200:203], off offset:576 sc1
	v_add_co_u32_e32 v224, vcc, 0x160000, v220
	s_nop 1
	v_addc_co_u32_e32 v225, vcc, 0, v221, vcc
	global_load_dwordx4 v[188:191], v[224:225], off
	global_load_dwordx4 v[192:195], v[224:225], off offset:64
	global_load_dwordx4 v[196:199], v[224:225], off offset:512
	global_load_dwordx4 v[200:203], v[224:225], off offset:576
	s_waitcnt vmcnt(16)
	v_add_co_u32_e32 v226, vcc, 0x120000, v222
	s_nop 1
	v_addc_co_u32_e32 v227, vcc, 0, v223, vcc
	v_pk_fma_f32 v[206:207], v[54:55], v[142:143], v[206:207]
	v_pk_fma_f32 v[204:205], v[52:53], v[140:141], v[204:205]
	global_store_dwordx4 v[226:227], v[204:207], off sc1
	v_pk_fma_f32 v[210:211], v[50:51], v[138:139], v[210:211]
	v_pk_fma_f32 v[208:209], v[48:49], v[136:137], v[208:209]
	global_store_dwordx4 v[226:227], v[208:211], off offset:64 sc1
	v_pk_fma_f32 v[214:215], v[38:39], v[134:135], v[214:215]
	v_pk_fma_f32 v[212:213], v[36:37], v[132:133], v[212:213]
	global_store_dwordx4 v[226:227], v[212:215], off offset:512 sc1
	v_pk_fma_f32 v[218:219], v[34:35], v[130:131], v[218:219]
	v_pk_fma_f32 v[216:217], v[32:33], v[128:129], v[216:217]
	global_store_dwordx4 v[226:227], v[216:219], off offset:576 sc1
	s_waitcnt vmcnt(12)
	v_add_co_u32_e32 v226, vcc, 0x140000, v222
	s_nop 1
	v_addc_co_u32_e32 v227, vcc, 0, v223, vcc
	v_pk_fma_f32 v[174:175], v[30:31], v[142:143], v[174:175]
	v_pk_fma_f32 v[172:173], v[28:29], v[140:141], v[172:173]
	global_store_dwordx4 v[226:227], v[172:175], off sc1
	v_pk_fma_f32 v[178:179], v[26:27], v[138:139], v[178:179]
	v_pk_fma_f32 v[176:177], v[24:25], v[136:137], v[176:177]
	global_store_dwordx4 v[226:227], v[176:179], off offset:64 sc1
	v_pk_fma_f32 v[182:183], v[14:15], v[134:135], v[182:183]
	v_pk_fma_f32 v[180:181], v[12:13], v[132:133], v[180:181]
	global_store_dwordx4 v[226:227], v[180:183], off offset:512 sc1
	v_pk_fma_f32 v[186:187], v[10:11], v[130:131], v[186:187]
	v_pk_fma_f32 v[184:185], v[8:9], v[128:129], v[184:185]
	global_store_dwordx4 v[226:227], v[184:187], off offset:576 sc1
	s_waitcnt vmcnt(8)
	v_add_co_u32_e32 v226, vcc, 0x160000, v222
	s_nop 1
	v_addc_co_u32_e32 v227, vcc, 0, v223, vcc
	v_pk_fma_f32 v[190:191], v[22:23], v[142:143], v[190:191]
	v_pk_fma_f32 v[188:189], v[20:21], v[140:141], v[188:189]
	global_store_dwordx4 v[226:227], v[188:191], off sc1
	v_pk_fma_f32 v[194:195], v[18:19], v[138:139], v[194:195]
	v_pk_fma_f32 v[192:193], v[16:17], v[136:137], v[192:193]
	global_store_dwordx4 v[226:227], v[192:195], off offset:64 sc1
	v_pk_fma_f32 v[198:199], v[6:7], v[134:135], v[198:199]
	v_pk_fma_f32 v[196:197], v[4:5], v[132:133], v[196:197]
	global_store_dwordx4 v[226:227], v[196:199], off offset:512 sc1
	v_pk_fma_f32 v[202:203], v[2:3], v[130:131], v[202:203]
	v_pk_fma_f32 v[200:201], v[0:1], v[128:129], v[200:201]
	global_store_dwordx4 v[226:227], v[200:203], off offset:576 sc1
	s_cbranch_execnz .LBB0_885

;     __device__ __forceinline__ void operator()(const f32x4 (&acc)[2][2][4][2], const Unit& u, int wr, int wc, int fr, int fq) const {
;     ...
;         int woff = row0 * D + col0; asm volatile("" : "+v"(woff));
;         f32x4 gw[2][2], ww[2][2];
; #pragma unroll
;         for (int bj = 0; bj < 2; ++bj)
; #pragma unroll
;             for (int n = 0; n < 2; ++n) { gw[bj][n] = *(const f32x4*)(gp + (col0 + bj * HALF + n * 16)); ww[bj][n] = *(const f32x4*)(nw + (col0 + bj * HALF + n * 16)); }
; #pragma unroll
;         for (int am = 0; am < 4; ++am) { f32x4 rv[2][2][2]; float rr[2];
; #pragma unroll
;             for (int m2 = 0; m2 < 2; ++m2) { rr[m2] = red[1024 + (am >> 1) * HALF + wr * 64 + ((am & 1) * 2 + m2) * 16 + fr];
; #pragma unroll
;                 for (int bj = 0; bj < 2; ++bj)
; #pragma unroll
;                     for (int n = 0; n < 2; ++n) rv[m2][bj][n] = *(const f32x4*)(res0 + (woff + ((am >> 1) * HALF + ((am & 1) * 2 + m2) * 16) * D + bj * HALF + n * 16)); }
; #pragma unroll
;             for (int m2 = 0; m2 < 2; ++m2)
; #pragma unroll
;                 for (int bj = 0; bj < 2; ++bj)
; #pragma unroll
;                     for (int n = 0; n < 2; ++n) *(f32x4*)(out + (woff + ((am >> 1) * HALF + ((am & 1) * 2 + m2) * 16) * D + bj * HALF + n * 16)) = (rv[m2][bj][n] + gw[bj][n] * acc[am >> 1][bj][(am & 1) * 2 + m2][n]) * rr[m2] * ww[bj][n]; }
.LBB0_1181:
	s_or_b64 exec, exec, s[30:31]
	s_waitcnt lgkmcnt(0)
	s_barrier
	v_readlane_b32 s70, v245, 9
	v_readlane_b32 s71, v245, 10
	s_nop 3
	v_lshl_add_u64 v[144:145], v[174:175], 2, s[70:71]
	global_load_dwordx4 v[208:211], v[144:145], off
	global_load_dwordx4 v[212:215], v[144:145], off offset:64
	global_load_dwordx4 v[216:219], v[144:145], off offset:512
	global_load_dwordx4 v[220:223], v[144:145], off offset:576
	ds_read2_b32 v[192:193], v180 offset1:16
	ds_read2_b32 v[194:195], v180 offset0:32 offset1:48
	ds_read2_b32 v[196:197], v181 offset1:16
	ds_read2_b32 v[198:199], v181 offset0:32 offset1:48
	v_readlane_b32 s64, v245, 21
	v_readlane_b32 s65, v245, 22
	v_readlane_b32 s66, v245, 23
	v_readlane_b32 s67, v245, 24
	v_readlane_b32 s68, v245, 25
	v_readlane_b32 s69, v245, 26
	v_readlane_b32 s70, v245, 27
	v_readlane_b32 s71, v245, 28
	v_readlane_b32 s72, v245, 29
	v_readlane_b32 s73, v245, 30
	v_readlane_b32 s74, v245, 31
	v_readlane_b32 s75, v245, 32
	v_readlane_b32 s76, v245, 33
	v_readlane_b32 s77, v245, 34
	v_readlane_b32 s78, v245, 35
	v_readlane_b32 s79, v245, 36
	s_nop 3
	s_mov_b64 s[26:27], s[78:79]
	s_mov_b64 s[34:35], 0
	s_mov_b64 s[30:31], s[78:79]
	v_ashrrev_i32_e32 v173, 31, v172
	v_lshlrev_b64 v[224:225], 2, v[172:173]
	v_lshl_add_u64 v[224:225], s[26:27], 0, v[224:225]
	s_waitcnt vmcnt(0) lgkmcnt(0)
	v_pk_mul_f32 v[124:125], v[192:193], v[124:125] op_sel_hi:[0,1]
	v_pk_mul_f32 v[126:127], v[192:193], v[126:127] op_sel_hi:[0,1]
	v_pk_mul_f32 v[124:125], v[208:209], v[124:125]
	v_pk_mul_f32 v[126:127], v[210:211], v[126:127]
	global_store_dwordx4 v[224:225], v[124:127], off sc1
	v_pk_mul_f32 v[120:121], v[192:193], v[120:121] op_sel_hi:[0,1]
	v_pk_mul_f32 v[122:123], v[192:193], v[122:123] op_sel_hi:[0,1]
	v_pk_mul_f32 v[120:121], v[212:213], v[120:121]
	v_pk_mul_f32 v[122:123], v[214:215], v[122:123]
	global_store_dwordx4 v[224:225], v[120:123], off offset:64 sc1
	v_pk_mul_f32 v[108:109], v[192:193], v[108:109] op_sel_hi:[0,1]
	v_pk_mul_f32 v[110:111], v[192:193], v[110:111] op_sel_hi:[0,1]
	v_pk_mul_f32 v[108:109], v[216:217], v[108:109]
	v_pk_mul_f32 v[110:111], v[218:219], v[110:111]
	global_store_dwordx4 v[224:225], v[108:111], off offset:512 sc1
	v_pk_mul_f32 v[104:105], v[192:193], v[104:105] op_sel_hi:[0,1]
	v_pk_mul_f32 v[106:107], v[192:193], v[106:107] op_sel_hi:[0,1]
	v_pk_mul_f32 v[104:105], v[220:221], v[104:105]
	v_pk_mul_f32 v[106:107], v[222:223], v[106:107]
	global_store_dwordx4 v[224:225], v[104:107], off offset:576 sc1
	v_add_co_u32_e32 v226, vcc, 0x20000, v224
	s_nop 1
	v_addc_co_u32_e32 v227, vcc, 0, v225, vcc
	v_pk_mul_f32 v[116:117], v[192:193], v[116:117] op_sel:[1,0]
	v_pk_mul_f32 v[118:119], v[192:193], v[118:119] op_sel:[1,0]
	v_pk_mul_f32 v[116:117], v[208:209], v[116:117]
	v_pk_mul_f32 v[118:119], v[210:211], v[118:119]
	global_store_dwordx4 v[226:227], v[116:119], off sc1
	v_pk_mul_f32 v[112:113], v[192:193], v[112:113] op_sel:[1,0]
	v_pk_mul_f32 v[114:115], v[192:193], v[114:115] op_sel:[1,0]
	v_pk_mul_f32 v[112:113], v[212:213], v[112:113]
	v_pk_mul_f32 v[114:115], v[214:215], v[114:115]
	global_store_dwordx4 v[226:227], v[112:115], off offset:64 sc1
	v_pk_mul_f32 v[100:101], v[192:193], v[100:101] op_sel:[1,0]
	v_pk_mul_f32 v[102:103], v[192:193], v[102:103] op_sel:[1,0]
	v_pk_mul_f32 v[100:101], v[216:217], v[100:101]
	v_pk_mul_f32 v[102:103], v[218:219], v[102:103]
	global_store_dwordx4 v[226:227], v[100:103], off offset:512 sc1
	v_pk_mul_f32 v[96:97], v[192:193], v[96:97] op_sel:[1,0]
	v_pk_mul_f32 v[98:99], v[192:193], v[98:99] op_sel:[1,0]
	v_pk_mul_f32 v[96:97], v[220:221], v[96:97]
	v_pk_mul_f32 v[98:99], v[222:223], v[98:99]
	global_store_dwordx4 v[226:227], v[96:99], off offset:576 sc1
	v_add_co_u32_e32 v226, vcc, 0x40000, v224
	s_nop 1
	v_addc_co_u32_e32 v227, vcc, 0, v225, vcc
	v_pk_mul_f32 v[92:93], v[194:195], v[92:93] op_sel_hi:[0,1]
	v_pk_mul_f32 v[94:95], v[194:195], v[94:95] op_sel_hi:[0,1]
	v_pk_mul_f32 v[92:93], v[208:209], v[92:93]
	v_pk_mul_f32 v[94:95], v[210:211], v[94:95]
	global_store_dwordx4 v[226:227], v[92:95], off sc1
	v_pk_mul_f32 v[88:89], v[194:195], v[88:89] op_sel_hi:[0,1]
	v_pk_mul_f32 v[90:91], v[194:195], v[90:91] op_sel_hi:[0,1]
	v_pk_mul_f32 v[88:89], v[212:213], v[88:89]
	v_pk_mul_f32 v[90:91], v[214:215], v[90:91]
	global_store_dwordx4 v[226:227], v[88:91], off offset:64 sc1
	v_pk_mul_f32 v[76:77], v[194:195], v[76:77] op_sel_hi:[0,1]
	v_pk_mul_f32 v[78:79], v[194:195], v[78:79] op_sel_hi:[0,1]
	v_pk_mul_f32 v[76:77], v[216:217], v[76:77]
	v_pk_mul_f32 v[78:79], v[218:219], v[78:79]
	global_store_dwordx4 v[226:227], v[76:79], off offset:512 sc1
	v_pk_mul_f32 v[72:73], v[194:195], v[72:73] op_sel_hi:[0,1]
	v_pk_mul_f32 v[74:75], v[194:195], v[74:75] op_sel_hi:[0,1]
	v_pk_mul_f32 v[72:73], v[220:221], v[72:73]
	v_pk_mul_f32 v[74:75], v[222:223], v[74:75]
	global_store_dwordx4 v[226:227], v[72:75], off offset:576 sc1
	v_add_co_u32_e32 v226, vcc, 0x60000, v224
	s_nop 1
	v_addc_co_u32_e32 v227, vcc, 0, v225, vcc
	v_pk_mul_f32 v[84:85], v[194:195], v[84:85] op_sel:[1,0]
	v_pk_mul_f32 v[86:87], v[194:195], v[86:87] op_sel:[1,0]
	v_pk_mul_f32 v[84:85], v[208:209], v[84:85]
	v_pk_mul_f32 v[86:87], v[210:211], v[86:87]
	global_store_dwordx4 v[226:227], v[84:87], off sc1
	v_pk_mul_f32 v[80:81], v[194:195], v[80:81] op_sel:[1,0]
;     __device__ __forceinline__ void operator()(const f32x4 (&acc)[2][2][4][2], const Unit& u, int wr, int wc, int fr, int fq) const {
;     ...
;         for (int am = 0; am < 4; ++am) { f32x4 rv[2][2][2]; float rr[2];
; #pragma unroll
;             for (int m2 = 0; m2 < 2; ++m2) { rr[m2] = red[1024 + (am >> 1) * HALF + wr * 64 + ((am & 1) * 2 + m2) * 16 + fr];
; #pragma unroll
;                 for (int bj = 0; bj < 2; ++bj)
; #pragma unroll
;                     for (int n = 0; n < 2; ++n) rv[m2][bj][n] = *(const f32x4*)(res0 + (woff + ((am >> 1) * HALF + ((am & 1) * 2 + m2) * 16) * D + bj * HALF + n * 16)); }
; #pragma unroll
;             for (int m2 = 0; m2 < 2; ++m2)
; #pragma unroll
;                 for (int bj = 0; bj < 2; ++bj)
; #pragma unroll
;                     for (int n = 0; n < 2; ++n) *(f32x4*)(out + (woff + ((am >> 1) * HALF + ((am & 1) * 2 + m2) * 16) * D + bj * HALF + n * 16)) = (rv[m2][bj][n] + gw[bj][n] * acc[am >> 1][bj][(am & 1) * 2 + m2][n]) * rr[m2] * ww[bj][n]; }
	v_pk_mul_f32 v[82:83], v[194:195], v[82:83] op_sel:[1,0]
	v_pk_mul_f32 v[80:81], v[212:213], v[80:81]
	v_pk_mul_f32 v[82:83], v[214:215], v[82:83]
	global_store_dwordx4 v[226:227], v[80:83], off offset:64 sc1
	v_pk_mul_f32 v[68:69], v[194:195], v[68:69] op_sel:[1,0]
	v_pk_mul_f32 v[70:71], v[194:195], v[70:71] op_sel:[1,0]
	v_pk_mul_f32 v[68:69], v[216:217], v[68:69]
	v_pk_mul_f32 v[70:71], v[218:219], v[70:71]
	global_store_dwordx4 v[226:227], v[68:71], off offset:512 sc1
	v_pk_mul_f32 v[64:65], v[194:195], v[64:65] op_sel:[1,0]
	v_pk_mul_f32 v[66:67], v[194:195], v[66:67] op_sel:[1,0]
	v_pk_mul_f32 v[64:65], v[220:221], v[64:65]
	v_pk_mul_f32 v[66:67], v[222:223], v[66:67]
	global_store_dwordx4 v[226:227], v[64:67], off offset:576 sc1
	v_add_co_u32_e32 v226, vcc, 0x100000, v224
	s_nop 1
	v_addc_co_u32_e32 v227, vcc, 0, v225, vcc
	v_pk_mul_f32 v[60:61], v[196:197], v[60:61] op_sel_hi:[0,1]
	v_pk_mul_f32 v[62:63], v[196:197], v[62:63] op_sel_hi:[0,1]
	v_pk_mul_f32 v[60:61], v[208:209], v[60:61]
	v_pk_mul_f32 v[62:63], v[210:211], v[62:63]
	global_store_dwordx4 v[226:227], v[60:63], off sc1
	v_pk_mul_f32 v[56:57], v[196:197], v[56:57] op_sel_hi:[0,1]
	v_pk_mul_f32 v[58:59], v[196:197], v[58:59] op_sel_hi:[0,1]
	v_pk_mul_f32 v[56:57], v[212:213], v[56:57]
	v_pk_mul_f32 v[58:59], v[214:215], v[58:59]
	global_store_dwordx4 v[226:227], v[56:59], off offset:64 sc1
	v_pk_mul_f32 v[44:45], v[196:197], v[44:45] op_sel_hi:[0,1]
	v_pk_mul_f32 v[46:47], v[196:197], v[46:47] op_sel_hi:[0,1]
	v_pk_mul_f32 v[44:45], v[216:217], v[44:45]
	v_pk_mul_f32 v[46:47], v[218:219], v[46:47]
	global_store_dwordx4 v[226:227], v[44:47], off offset:512 sc1
	v_pk_mul_f32 v[40:41], v[196:197], v[40:41] op_sel_hi:[0,1]
	v_pk_mul_f32 v[42:43], v[196:197], v[42:43] op_sel_hi:[0,1]
	v_pk_mul_f32 v[40:41], v[220:221], v[40:41]
	v_pk_mul_f32 v[42:43], v[222:223], v[42:43]
	global_store_dwordx4 v[226:227], v[40:43], off offset:576 sc1
	v_add_co_u32_e32 v226, vcc, 0x120000, v224
	s_nop 1
	v_addc_co_u32_e32 v227, vcc, 0, v225, vcc
	v_pk_mul_f32 v[52:53], v[196:197], v[52:53] op_sel:[1,0]
	v_pk_mul_f32 v[54:55], v[196:197], v[54:55] op_sel:[1,0]
	v_pk_mul_f32 v[52:53], v[208:209], v[52:53]
	v_pk_mul_f32 v[54:55], v[210:211], v[54:55]
	global_store_dwordx4 v[226:227], v[52:55], off sc1
	v_pk_mul_f32 v[48:49], v[196:197], v[48:49] op_sel:[1,0]
	v_pk_mul_f32 v[50:51], v[196:197], v[50:51] op_sel:[1,0]
	v_pk_mul_f32 v[48:49], v[212:213], v[48:49]
	v_pk_mul_f32 v[50:51], v[214:215], v[50:51]
	global_store_dwordx4 v[226:227], v[48:51], off offset:64 sc1
	v_pk_mul_f32 v[36:37], v[196:197], v[36:37] op_sel:[1,0]
	v_pk_mul_f32 v[38:39], v[196:197], v[38:39] op_sel:[1,0]
	v_pk_mul_f32 v[36:37], v[216:217], v[36:37]
	v_pk_mul_f32 v[38:39], v[218:219], v[38:39]
	global_store_dwordx4 v[226:227], v[36:39], off offset:512 sc1
	v_pk_mul_f32 v[32:33], v[196:197], v[32:33] op_sel:[1,0]
	v_pk_mul_f32 v[34:35], v[196:197], v[34:35] op_sel:[1,0]
	v_pk_mul_f32 v[32:33], v[220:221], v[32:33]
	v_pk_mul_f32 v[34:35], v[222:223], v[34:35]
	global_store_dwordx4 v[226:227], v[32:35], off offset:576 sc1
	v_add_co_u32_e32 v226, vcc, 0x140000, v224
	s_nop 1
	v_addc_co_u32_e32 v227, vcc, 0, v225, vcc
	v_pk_mul_f32 v[28:29], v[198:199], v[28:29] op_sel_hi:[0,1]
	v_pk_mul_f32 v[30:31], v[198:199], v[30:31] op_sel_hi:[0,1]
	v_pk_mul_f32 v[28:29], v[208:209], v[28:29]
	v_pk_mul_f32 v[30:31], v[210:211], v[30:31]
	global_store_dwordx4 v[226:227], v[28:31], off sc1
	v_pk_mul_f32 v[24:25], v[198:199], v[24:25] op_sel_hi:[0,1]
	v_pk_mul_f32 v[26:27], v[198:199], v[26:27] op_sel_hi:[0,1]
	v_pk_mul_f32 v[24:25], v[212:213], v[24:25]
	v_pk_mul_f32 v[26:27], v[214:215], v[26:27]
	global_store_dwordx4 v[226:227], v[24:27], off offset:64 sc1
	v_pk_mul_f32 v[12:13], v[198:199], v[12:13] op_sel_hi:[0,1]
	v_pk_mul_f32 v[14:15], v[198:199], v[14:15] op_sel_hi:[0,1]
	v_pk_mul_f32 v[12:13], v[216:217], v[12:13]
	v_pk_mul_f32 v[14:15], v[218:219], v[14:15]
	global_store_dwordx4 v[226:227], v[12:15], off offset:512 sc1
	v_pk_mul_f32 v[8:9], v[198:199], v[8:9] op_sel_hi:[0,1]
	v_pk_mul_f32 v[10:11], v[198:199], v[10:11] op_sel_hi:[0,1]
	v_pk_mul_f32 v[8:9], v[220:221], v[8:9]
	v_pk_mul_f32 v[10:11], v[222:223], v[10:11]
	global_store_dwordx4 v[226:227], v[8:11], off offset:576 sc1
	v_add_co_u32_e32 v226, vcc, 0x160000, v224
	s_nop 1
	v_addc_co_u32_e32 v227, vcc, 0, v225, vcc
	v_pk_mul_f32 v[20:21], v[198:199], v[20:21] op_sel:[1,0]
	v_pk_mul_f32 v[22:23], v[198:199], v[22:23] op_sel:[1,0]
	v_pk_mul_f32 v[20:21], v[208:209], v[20:21]
	v_pk_mul_f32 v[22:23], v[210:211], v[22:23]
	global_store_dwordx4 v[226:227], v[20:23], off sc1
	v_pk_mul_f32 v[16:17], v[198:199], v[16:17] op_sel:[1,0]
	v_pk_mul_f32 v[18:19], v[198:199], v[18:19] op_sel:[1,0]
	v_pk_mul_f32 v[16:17], v[212:213], v[16:17]
	v_pk_mul_f32 v[18:19], v[214:215], v[18:19]
	global_store_dwordx4 v[226:227], v[16:19], off offset:64 sc1
	v_pk_mul_f32 v[4:5], v[198:199], v[4:5] op_sel:[1,0]
	v_pk_mul_f32 v[6:7], v[198:199], v[6:7] op_sel:[1,0]
	v_pk_mul_f32 v[4:5], v[216:217], v[4:5]
	v_pk_mul_f32 v[6:7], v[218:219], v[6:7]
	global_store_dwordx4 v[226:227], v[4:7], off offset:512 sc1
	v_pk_mul_f32 v[128:129], v[198:199], v[0:1] op_sel:[1,0]
	v_pk_mul_f32 v[130:131], v[198:199], v[2:3] op_sel:[1,0]
	v_pk_mul_f32 v[128:129], v[220:221], v[128:129]
	v_pk_mul_f32 v[130:131], v[222:223], v[130:131]

;     __device__ __forceinline__ void operator()(const f32x4 (&acc)[2][2][4][2], const Unit& u, int wr, int wc, int fr, int fq) const {
;     ...
;             for (int m2 = 0; m2 < 2; ++m2)
; #pragma unroll
;                 for (int bj = 0; bj < 2; ++bj)
; #pragma unroll
;                     for (int n = 0; n < 2; ++n) *(f32x4*)(out + (woff + ((am >> 1) * HALF + ((am & 1) * 2 + m2) * 16) * D + bj * HALF + n * 16)) = (rv[m2][bj][n] + gw[bj][n] * acc[am >> 1][bj][(am & 1) * 2 + m2][n]) * rr[m2] * ww[bj][n]; }
.LBB0_1184:
	v_add_u32_e32 v0, 0x58090, v172
	v_ashrrev_i32_e32 v1, 31, v0
	v_lshl_add_u64 v[0:1], v[0:1], 2, s[30:31]
	s_and_b64 vcc, exec, s[4:5]
	s_mov_b64 s[4:5], -1
	global_store_dwordx4 v[0:1], v[128:131], off sc1
	s_cbranch_vccnz .LBB0_1130
	s_andn2_b64 vcc, exec, s[16:17]
	s_cbranch_vccnz .LBB0_1129
	s_barrier
	s_branch .LBB0_1129
